# packed softmax variant with extra distance before the last consumer of exp results
# speedup vs baseline: 1.0099x; 1.0024x over previous
.LBB0_582:
	v_pk_add_f32 v[134:135], v[134:135], v[224:225] op_sel_hi:[1,0] neg_lo:[0,1] neg_hi:[0,1]
	v_pk_add_f32 v[136:137], v[136:137], v[224:225] op_sel_hi:[1,0] neg_lo:[0,1] neg_hi:[0,1]
	v_exp_f32_e32 v134, v134
	v_exp_f32_e32 v135, v135
	v_pk_add_f32 v[138:139], v[138:139], v[224:225] op_sel_hi:[1,0] neg_lo:[0,1] neg_hi:[0,1]
	v_exp_f32_e32 v136, v136
	v_exp_f32_e32 v137, v137
	v_pk_add_f32 v[140:141], v[140:141], v[224:225] op_sel_hi:[1,0] neg_lo:[0,1] neg_hi:[0,1]
	v_exp_f32_e32 v138, v138
	v_exp_f32_e32 v139, v139
	v_pk_add_f32 v[234:235], v[146:147], v[224:225] op_sel_hi:[1,0] neg_lo:[0,1] neg_hi:[0,1]
	v_pk_add_f32 v[246:247], v[134:135], v[136:137]
	v_exp_f32_e32 v140, v140
	v_exp_f32_e32 v141, v141
	v_pk_add_f32 v[236:237], v[148:149], v[224:225] op_sel_hi:[1,0] neg_lo:[0,1] neg_hi:[0,1]
	v_pk_add_f32 v[246:247], v[246:247], v[138:139]
	v_exp_f32_e32 v234, v234
	v_exp_f32_e32 v235, v235
	v_pk_add_f32 v[238:239], v[142:143], v[224:225] op_sel_hi:[1,0] neg_lo:[0,1] neg_hi:[0,1]
	v_pk_add_f32 v[246:247], v[246:247], v[140:141]
	v_exp_f32_e32 v236, v236
	v_exp_f32_e32 v237, v237
	v_pk_add_f32 v[244:245], v[144:145], v[224:225] op_sel_hi:[1,0] neg_lo:[0,1] neg_hi:[0,1]
	v_pk_add_f32 v[246:247], v[246:247], v[234:235]
	v_exp_f32_e32 v238, v238
	v_exp_f32_e32 v239, v239
	v_pk_add_f32 v[226:227], v[150:151], v[222:223] op_sel:[0,1] op_sel_hi:[1,1] neg_lo:[0,1] neg_hi:[0,1]
	v_pk_add_f32 v[246:247], v[246:247], v[236:237]
	v_exp_f32_e32 v244, v244
	v_exp_f32_e32 v245, v245
	v_pk_add_f32 v[228:229], v[152:153], v[222:223] op_sel:[0,1] op_sel_hi:[1,1] neg_lo:[0,1] neg_hi:[0,1]
	v_pk_add_f32 v[246:247], v[246:247], v[238:239]
	v_exp_f32_e32 v226, v226
	v_exp_f32_e32 v227, v227
	v_pk_add_f32 v[230:231], v[154:155], v[222:223] op_sel:[0,1] op_sel_hi:[1,1] neg_lo:[0,1] neg_hi:[0,1]
	v_pk_add_f32 v[246:247], v[246:247], v[244:245]
	v_exp_f32_e32 v228, v228
	v_exp_f32_e32 v229, v229
	v_pk_add_f32 v[232:233], v[156:157], v[222:223] op_sel:[0,1] op_sel_hi:[1,1] neg_lo:[0,1] neg_hi:[0,1]
	v_exp_f32_e32 v230, v230
	v_exp_f32_e32 v231, v231
	v_pk_add_f32 v[158:159], v[158:159], v[222:223] op_sel:[0,1] op_sel_hi:[1,1] neg_lo:[0,1] neg_hi:[0,1]
	v_pk_add_f32 v[248:249], v[226:227], v[228:229]
	v_exp_f32_e32 v232, v232
	v_exp_f32_e32 v233, v233
	v_pk_add_f32 v[160:161], v[160:161], v[222:223] op_sel:[0,1] op_sel_hi:[1,1] neg_lo:[0,1] neg_hi:[0,1]
	v_pk_add_f32 v[248:249], v[248:249], v[230:231]
	v_exp_f32_e32 v158, v158
	v_exp_f32_e32 v159, v159
	v_pk_add_f32 v[162:163], v[162:163], v[222:223] op_sel:[0,1] op_sel_hi:[1,1] neg_lo:[0,1] neg_hi:[0,1]
	v_pk_add_f32 v[248:249], v[248:249], v[232:233]
	v_exp_f32_e32 v160, v160
	v_exp_f32_e32 v161, v161
	v_pk_add_f32 v[164:165], v[164:165], v[222:223] op_sel:[0,1] op_sel_hi:[1,1] neg_lo:[0,1] neg_hi:[0,1]
	v_pk_add_f32 v[248:249], v[248:249], v[158:159]
	v_exp_f32_e32 v162, v162
	v_exp_f32_e32 v163, v163
	v_pk_add_f32 v[248:249], v[248:249], v[160:161]
	v_exp_f32_e32 v164, v164
	v_exp_f32_e32 v165, v165
	v_pk_add_f32 v[248:249], v[248:249], v[162:163]
	v_add_f32_e32 v241, v246, v247
	v_fmac_f32_e32 v241, v191, v208
	s_nop 1
	v_pk_add_f32 v[248:249], v[248:249], v[164:165]
	v_add_f32_e32 v191, v248, v249
	s_mul_i32 s0, s24, 0x4800
	v_fmac_f32_e32 v191, v203, v206
	v_add_u32_e32 v203, s0, v197
	v_cvt_pk_bf16_f32 v154, v158, v159
	v_add_u32_e32 v206, 0xc800, v203
	v_add_u32_e32 v158, 0xd000, v203
	v_cvt_pk_bf16_f32 v155, v160, v161
	v_cvt_pk_bf16_f32 v134, v134, v135
	v_cvt_pk_bf16_f32 v135, v136, v137
	v_cvt_pk_bf16_f32 v136, v138, v139
	v_cvt_pk_bf16_f32 v137, v140, v141
	ds_read2_b64 v[138:141], v206 offset1:4
	ds_read2_b64 v[142:145], v206 offset0:8 offset1:12
	ds_read2_b64 v[146:149], v158 offset0:32 offset1:36
	ds_read2_b64 v[158:161], v158 offset0:40 offset1:44
	v_cvt_pk_bf16_f32 v150, v226, v227
	v_cvt_pk_bf16_f32 v151, v228, v229
	v_cvt_pk_bf16_f32 v152, v230, v231
	v_cvt_pk_bf16_f32 v153, v232, v233
	v_cvt_pk_bf16_f32 v156, v162, v163
	v_cvt_pk_bf16_f32 v157, v164, v165
	v_cvt_pk_bf16_f32 v162, v234, v235
	v_cvt_pk_bf16_f32 v163, v236, v237
	v_cvt_pk_bf16_f32 v164, v238, v239
	v_cvt_pk_bf16_f32 v165, v244, v245
	s_waitcnt lgkmcnt(3)
	v_mfma_f32_16x16x32_bf16 v[62:65], v[138:141], v[150:153], v[62:65]
	v_mfma_f32_16x16x32_bf16 v[30:33], v[138:141], v[134:137], v[30:33]
	s_waitcnt lgkmcnt(2)
	v_mfma_f32_16x16x32_bf16 v[62:65], v[142:145], v[154:157], v[62:65]
	v_mfma_f32_16x16x32_bf16 v[30:33], v[142:145], v[162:165], v[30:33]
	v_add_u32_e32 v142, 0xd800, v203
	ds_read2_b64 v[138:141], v142 offset0:64 offset1:68
	ds_read2_b64 v[142:145], v142 offset0:72 offset1:76
	s_waitcnt lgkmcnt(3)
	v_mfma_f32_16x16x32_bf16 v[58:61], v[146:149], v[150:153], v[58:61]
	v_mfma_f32_16x16x32_bf16 v[26:29], v[146:149], v[134:137], v[26:29]
	s_waitcnt lgkmcnt(2)
	v_mfma_f32_16x16x32_bf16 v[58:61], v[158:161], v[154:157], v[58:61]
	v_mfma_f32_16x16x32_bf16 v[26:29], v[158:161], v[162:165], v[26:29]
	v_add_u32_e32 v158, 0xe000, v203
	ds_read2_b64 v[146:149], v158 offset0:96 offset1:100
	ds_read2_b64 v[158:161], v158 offset0:104 offset1:108
	s_waitcnt lgkmcnt(3)
	v_mfma_f32_16x16x32_bf16 v[54:57], v[138:141], v[150:153], v[54:57]
	v_mfma_f32_16x16x32_bf16 v[22:25], v[138:141], v[134:137], v[22:25]
	s_waitcnt lgkmcnt(2)
	v_mfma_f32_16x16x32_bf16 v[54:57], v[142:145], v[154:157], v[54:57]
	v_mfma_f32_16x16x32_bf16 v[22:25], v[142:145], v[162:165], v[22:25]
	v_add_u32_e32 v142, 0xe800, v203
	ds_read2_b64 v[138:141], v142 offset0:128 offset1:132
	ds_read2_b64 v[142:145], v142 offset0:136 offset1:140
	s_waitcnt lgkmcnt(3)
	v_mfma_f32_16x16x32_bf16 v[50:53], v[146:149], v[150:153], v[50:53]
	v_mfma_f32_16x16x32_bf16 v[18:21], v[146:149], v[134:137], v[18:21]
	s_waitcnt lgkmcnt(2)
	v_mfma_f32_16x16x32_bf16 v[50:53], v[158:161], v[154:157], v[50:53]
	v_mfma_f32_16x16x32_bf16 v[18:21], v[158:161], v[162:165], v[18:21]
	v_add_u32_e32 v158, 0xf000, v203
	ds_read2_b64 v[146:149], v158 offset0:160 offset1:164
	ds_read2_b64 v[158:161], v158 offset0:168 offset1:172
	s_waitcnt lgkmcnt(3)
	v_mfma_f32_16x16x32_bf16 v[46:49], v[138:141], v[150:153], v[46:49]
	v_mfma_f32_16x16x32_bf16 v[14:17], v[138:141], v[134:137], v[14:17]
	s_waitcnt lgkmcnt(2)
	v_mfma_f32_16x16x32_bf16 v[46:49], v[142:145], v[154:157], v[46:49]
	v_mfma_f32_16x16x32_bf16 v[14:17], v[142:145], v[162:165], v[14:17]
	v_add_u32_e32 v142, 0xf800, v203
	ds_read2_b64 v[138:141], v142 offset0:192 offset1:196
	ds_read2_b64 v[142:145], v142 offset0:200 offset1:204
	s_waitcnt lgkmcnt(3)
	v_mfma_f32_16x16x32_bf16 v[42:45], v[146:149], v[150:153], v[42:45]
	v_mfma_f32_16x16x32_bf16 v[10:13], v[146:149], v[134:137], v[10:13]
	s_waitcnt lgkmcnt(2)
	v_mfma_f32_16x16x32_bf16 v[42:45], v[158:161], v[154:157], v[42:45]
	v_mfma_f32_16x16x32_bf16 v[10:13], v[158:161], v[162:165], v[10:13]
	v_add_u32_e32 v158, 0x3800, v206
	ds_read2_b64 v[146:149], v158 offset0:224 offset1:228
	ds_read2_b64 v[158:161], v158 offset0:232 offset1:236
	s_waitcnt lgkmcnt(3)
	v_mfma_f32_16x16x32_bf16 v[38:41], v[138:141], v[150:153], v[38:41]
	v_mfma_f32_16x16x32_bf16 v[6:9], v[138:141], v[134:137], v[6:9]
	s_waitcnt lgkmcnt(2)
	v_mfma_f32_16x16x32_bf16 v[38:41], v[142:145], v[154:157], v[38:41]
	v_mfma_f32_16x16x32_bf16 v[6:9], v[142:145], v[162:165], v[6:9]
	s_waitcnt lgkmcnt(1)
	v_mfma_f32_16x16x32_bf16 v[34:37], v[146:149], v[150:153], v[34:37]
	v_mfma_f32_16x16x32_bf16 v[2:5], v[146:149], v[134:137], v[2:5]
	s_waitcnt lgkmcnt(0)
	v_mfma_f32_16x16x32_bf16 v[34:37], v[158:161], v[154:157], v[34:37]
	v_mfma_f32_16x16x32_bf16 v[2:5], v[158:161], v[162:165], v[2:5]
	v_mov_b32_e32 v203, v191
	v_mov_b32_e32 v191, v241
	s_andn2_b64 vcc, exec, s[6:7]
	s_mov_b64 s[0:1], -1
	s_cbranch_vccz .LBB0_584
	s_branch .LBB0_585
